# final RMSNorm row loop de-serialised: 8 row loads issued together behind one wait instead of load-wait-store ladder (8 store-completion waits per row removed)
# speedup vs baseline: 1.0044x; 1.0044x over previous
; __global__ void __launch_bounds__(NWAVES * 64, 2) fwd_megakernel(Args args) {
;     ...
;         for (int k_ = 0; k_ < 8; ++k_) { const int m = pm0 * 256 + (bx >> 6) * 64 + wave * 8 + k_;
;             float sq = (lane < 32) ? PART[((size_t)(m >> 8) * 32 + lane) * 256 + (m & 255)] : 0.f;
;             sq = wave_sum(sq);
;             const float rstd = 1.0f / sqrtf(sq * (1.f / DM) + EPS);
;             const unsigned long long* xr = (const unsigned long long*)(XN + (size_t)m * DM) + lane;
;             f32x4* orow = (f32x4*)(out + (size_t)m * DM) + lane;
; #pragma unroll
;             for (int j = 0; j < 8; ++j) { const unsigned long long w = xr[64 * j]; const unsigned lo = (unsigned)w, hi = (unsigned)(w >> 32);
;                 f32x4 v = {__uint_as_float(lo << 16), __uint_as_float(lo & 0xffff0000u), __uint_as_float(hi << 16), __uint_as_float(hi & 0xffff0000u)};
;                 __builtin_nontemporal_store(v * rstd * gv[j], orow + 64 * j); }
;         }
.LBB0_443:
	s_or_b64 exec, exec, s[2:3]
	v_lshl_add_u64 v[42:43], s[14:15], 0, v[36:37]
	v_add_co_u32_e32 v44, vcc, s10, v42
	s_waitcnt vmcnt(0)
	ds_bpermute_b32 v41, v190, v40
	v_addc_co_u32_e32 v45, vcc, 0, v43, vcc
	global_load_dwordx2 v[52:53], v[44:45], off
	global_load_dwordx2 v[54:55], v[44:45], off offset:512
	global_load_dwordx2 v[56:57], v[44:45], off offset:1024
	global_load_dwordx2 v[58:59], v[44:45], off offset:1536
	global_load_dwordx2 v[60:61], v[44:45], off offset:2048
	global_load_dwordx2 v[62:63], v[44:45], off offset:2560
	global_load_dwordx2 v[64:65], v[44:45], off offset:3072
	global_load_dwordx2 v[66:67], v[44:45], off offset:3584
	v_lshl_add_u64 v[34:35], v[34:35], 0, 4
	s_waitcnt lgkmcnt(0)
	v_add_f32_e32 v40, v40, v41
	ds_bpermute_b32 v41, v205, v40
	v_lshl_add_u64 v[36:37], v[36:37], 0, s[6:7]
	s_waitcnt lgkmcnt(0)
	v_add_f32_e32 v40, v40, v41
	ds_bpermute_b32 v41, v206, v40
	s_waitcnt lgkmcnt(0)
	v_add_f32_e32 v40, v40, v41
	ds_bpermute_b32 v41, v207, v40
	s_waitcnt lgkmcnt(0)
	v_add_f32_e32 v40, v40, v41
	ds_bpermute_b32 v41, v208, v40
	s_waitcnt lgkmcnt(0)
	v_add_f32_e32 v40, v40, v41
	ds_bpermute_b32 v41, v209, v40
	s_waitcnt lgkmcnt(0)
	v_add_f32_e32 v40, v40, v41
	v_fmamk_f32 v40, v40, 0x3a000000, v38
	v_mul_f32_e32 v41, 0x4f800000, v40
	v_cmp_gt_f32_e32 vcc, s9, v40
	s_nop 1
	v_cndmask_b32_e32 v40, v40, v41, vcc
	v_sqrt_f32_e32 v41, v40
	s_nop 0
	v_add_u32_e32 v46, -1, v41
	v_add_u32_e32 v47, 1, v41
	v_fma_f32 v48, -v46, v41, v40
	v_fma_f32 v49, -v47, v41, v40
	v_cmp_ge_f32_e64 s[2:3], 0, v48
	s_nop 1
	v_cndmask_b32_e64 v41, v41, v46, s[2:3]
	v_cmp_lt_f32_e64 s[2:3], 0, v49
	s_nop 1
	v_cndmask_b32_e64 v41, v41, v47, s[2:3]
	v_mul_f32_e32 v46, 0x37800000, v41
	v_cndmask_b32_e32 v41, v41, v46, vcc
	v_cmp_class_f32_e32 vcc, v40, v39
	v_lshl_add_u64 v[46:47], v[32:33], 0, s[4:5]
	s_add_u32 s4, s4, 0x2000
	v_cndmask_b32_e32 v40, v41, v40, vcc
	v_div_scale_f32 v41, s[2:3], v40, v40, 1.0
	v_rcp_f32_e32 v48, v41
	v_div_scale_f32 v49, vcc, 1.0, v40, 1.0
	s_addc_u32 s5, s5, 0
	v_fma_f32 v50, -v41, v48, 1.0
	v_fmac_f32_e32 v48, v50, v48
	v_mul_f32_e32 v50, v49, v48
	v_fma_f32 v51, -v41, v50, v49
	v_fmac_f32_e32 v50, v51, v48
	v_fma_f32 v41, -v41, v50, v49
	v_div_fmas_f32 v41, v41, v48, v50
	v_div_fixup_f32 v48, v41, v40, 1.0
	s_cmp_eq_u32 s4, 0x10000
	s_waitcnt vmcnt(0)
	v_lshlrev_b32_e32 v40, 16, v52
	v_and_b32_e32 v41, 0xffff0000, v52
	v_lshlrev_b32_e32 v42, 16, v53
	v_and_b32_e32 v43, 0xffff0000, v53
	v_pk_mul_f32 v[40:41], v[48:49], v[40:41] op_sel_hi:[0,1]
	v_pk_mul_f32 v[42:43], v[48:49], v[42:43] op_sel_hi:[0,1]
	v_pk_mul_f32 v[40:41], v[0:1], v[40:41]
	v_pk_mul_f32 v[42:43], v[2:3], v[42:43]
	global_store_dwordx4 v[46:47], v[40:43], off nt
	v_lshlrev_b32_e32 v68, 16, v54
	v_and_b32_e32 v69, 0xffff0000, v54
	v_lshlrev_b32_e32 v70, 16, v55
	v_and_b32_e32 v71, 0xffff0000, v55
	v_pk_mul_f32 v[68:69], v[48:49], v[68:69] op_sel_hi:[0,1]
	v_pk_mul_f32 v[70:71], v[48:49], v[70:71] op_sel_hi:[0,1]
	v_pk_mul_f32 v[68:69], v[4:5], v[68:69]
	v_pk_mul_f32 v[70:71], v[6:7], v[70:71]
	global_store_dwordx4 v[46:47], v[68:71], off offset:1024 nt
	v_lshlrev_b32_e32 v40, 16, v56
	v_and_b32_e32 v41, 0xffff0000, v56
	v_lshlrev_b32_e32 v42, 16, v57
	v_and_b32_e32 v43, 0xffff0000, v57
	v_pk_mul_f32 v[40:41], v[48:49], v[40:41] op_sel_hi:[0,1]
	v_pk_mul_f32 v[42:43], v[48:49], v[42:43] op_sel_hi:[0,1]
	v_pk_mul_f32 v[40:41], v[8:9], v[40:41]
	v_pk_mul_f32 v[42:43], v[10:11], v[42:43]
	global_store_dwordx4 v[46:47], v[40:43], off offset:2048 nt
	v_lshlrev_b32_e32 v68, 16, v58
	v_and_b32_e32 v69, 0xffff0000, v58
	v_lshlrev_b32_e32 v70, 16, v59
	v_and_b32_e32 v71, 0xffff0000, v59
	v_pk_mul_f32 v[68:69], v[48:49], v[68:69] op_sel_hi:[0,1]
	v_pk_mul_f32 v[70:71], v[48:49], v[70:71] op_sel_hi:[0,1]
	v_pk_mul_f32 v[68:69], v[12:13], v[68:69]
	v_pk_mul_f32 v[70:71], v[14:15], v[70:71]
	global_store_dwordx4 v[46:47], v[68:71], off offset:3072 nt
	v_lshlrev_b32_e32 v40, 16, v60
	v_and_b32_e32 v41, 0xffff0000, v60
	v_lshlrev_b32_e32 v42, 16, v61
	v_and_b32_e32 v43, 0xffff0000, v61
	v_pk_mul_f32 v[40:41], v[48:49], v[40:41] op_sel_hi:[0,1]
	v_pk_mul_f32 v[42:43], v[48:49], v[42:43] op_sel_hi:[0,1]
	v_pk_mul_f32 v[40:41], v[16:17], v[40:41]
	v_pk_mul_f32 v[42:43], v[18:19], v[42:43]
	v_lshl_add_u64 v[46:47], v[46:47], 0, s[6:7]
	global_store_dwordx4 v[46:47], v[40:43], off nt
	v_lshlrev_b32_e32 v68, 16, v62
	v_and_b32_e32 v69, 0xffff0000, v62
	v_lshlrev_b32_e32 v70, 16, v63
	v_and_b32_e32 v71, 0xffff0000, v63
	v_pk_mul_f32 v[68:69], v[48:49], v[68:69] op_sel_hi:[0,1]
	v_pk_mul_f32 v[70:71], v[48:49], v[70:71] op_sel_hi:[0,1]
	v_pk_mul_f32 v[68:69], v[20:21], v[68:69]
	v_pk_mul_f32 v[70:71], v[22:23], v[70:71]
	global_store_dwordx4 v[46:47], v[68:71], off offset:1024 nt
	v_lshlrev_b32_e32 v40, 16, v64
	v_and_b32_e32 v41, 0xffff0000, v64
	v_lshlrev_b32_e32 v42, 16, v65
	v_and_b32_e32 v43, 0xffff0000, v65
	v_pk_mul_f32 v[40:41], v[48:49], v[40:41] op_sel_hi:[0,1]
	v_pk_mul_f32 v[42:43], v[48:49], v[42:43] op_sel_hi:[0,1]
	v_pk_mul_f32 v[40:41], v[24:25], v[40:41]
	v_pk_mul_f32 v[42:43], v[26:27], v[42:43]
	global_store_dwordx4 v[46:47], v[40:43], off offset:2048 nt
	v_lshlrev_b32_e32 v68, 16, v66
	v_and_b32_e32 v69, 0xffff0000, v66
	v_lshlrev_b32_e32 v70, 16, v67
	v_and_b32_e32 v71, 0xffff0000, v67
	v_pk_mul_f32 v[68:69], v[48:49], v[68:69] op_sel_hi:[0,1]
	v_pk_mul_f32 v[70:71], v[48:49], v[70:71] op_sel_hi:[0,1]
	v_pk_mul_f32 v[68:69], v[28:29], v[68:69]
	v_pk_mul_f32 v[70:71], v[30:31], v[70:71]
	global_store_dwordx4 v[46:47], v[68:71], off offset:3072 nt
	s_cbranch_scc1 .LBB0_446
